# v46 plus P6 combine rows issue their 15 loads up front with counted waits instead of load-wait-use one at a time
# baseline (speedup 1.0000x reference)
.LBB0_877:
	s_or_b64 exec, exec, s[18:19]
	v_lshl_add_u64 v[10:11], s[14:15], 0, v[4:5]
	v_lshl_add_u64 v[86:87], s[14:15], 0, v[2:3]
	s_add_i32 s12, s12, s86
	v_add_co_u32_e32 v80, vcc, 0x37843000, v10
	s_nop 1
	v_addc_co_u32_e32 v81, vcc, 0, v11, vcc
	global_load_dword v32, v[80:81], off
	v_add_co_u32_e32 v80, vcc, 0x37863000, v10
	s_nop 1
	v_addc_co_u32_e32 v81, vcc, 0, v11, vcc
	global_load_dword v33, v[80:81], off
	v_add_co_u32_e32 v80, vcc, 0x37883000, v10
	s_nop 1
	v_addc_co_u32_e32 v81, vcc, 0, v11, vcc
	global_load_dword v34, v[80:81], off
	v_add_co_u32_e32 v80, vcc, 0x3b8cb000, v10
	s_nop 1
	v_addc_co_u32_e32 v81, vcc, 0, v11, vcc
	global_load_dword v60, v[80:81], off
	v_add_co_u32_e32 v80, vcc, 0x3b8eb000, v10
	s_nop 1
	v_addc_co_u32_e32 v81, vcc, 0, v11, vcc
	global_load_dword v61, v[80:81], off
	v_add_co_u32_e32 v80, vcc, 0x34843000, v86
	s_nop 1
	v_addc_co_u32_e32 v81, vcc, 0, v87, vcc
	global_load_dwordx4 v[36:39], v[80:81], off
	global_load_dwordx4 v[40:43], v[80:81], off offset:16
	v_add_co_u32_e32 v80, vcc, 0x35843000, v86
	s_nop 1
	v_addc_co_u32_e32 v81, vcc, 0, v87, vcc
	global_load_dwordx4 v[44:47], v[80:81], off
	global_load_dwordx4 v[48:51], v[80:81], off offset:16
	v_add_co_u32_e32 v80, vcc, 0x36843000, v86
	s_nop 1
	v_addc_co_u32_e32 v81, vcc, 0, v87, vcc
	global_load_dwordx4 v[52:55], v[80:81], off
	global_load_dwordx4 v[56:59], v[80:81], off offset:16
	v_add_co_u32_e32 v80, vcc, 0x398cb000, v86
	s_nop 1
	v_addc_co_u32_e32 v81, vcc, 0, v87, vcc
	global_load_dwordx4 v[64:67], v[80:81], off
	global_load_dwordx4 v[72:75], v[80:81], off offset:16
	v_add_co_u32_e32 v80, vcc, 0x3a8cb000, v86
	s_nop 1
	v_addc_co_u32_e32 v81, vcc, 0, v87, vcc
	global_load_dwordx4 v[68:71], v[80:81], off
	global_load_dwordx4 v[76:79], v[80:81], off offset:16
	s_waitcnt vmcnt(12)
	v_max3_f32 v9, v32, v33, v34
	v_sub_f32_e32 v12, v32, v9
	v_mul_f32_e32 v12, 0x3fb8aa3b, v12
	v_sub_f32_e32 v13, v33, v9
	v_exp_f32_e32 v15, v12
	v_mul_f32_e32 v13, 0x3fb8aa3b, v13
	v_sub_f32_e32 v8, v34, v9
	v_exp_f32_e32 v28, v13
	v_mul_f32_e32 v8, 0x3fb8aa3b, v8
	v_exp_f32_e32 v29, v8
	v_add_f32_e32 v12, 0, v15
	v_add_f32_e32 v12, v12, v28
	v_add_f32_e32 v8, v12, v29
	v_div_scale_f32 v9, s[18:19], v8, v8, 1.0
	v_rcp_f32_e32 v12, v9
	s_nop 0
	v_fma_f32 v13, -v9, v12, 1.0
	v_fmac_f32_e32 v12, v13, v12
	v_div_scale_f32 v13, vcc, 1.0, v8, 1.0
	v_mul_f32_e32 v16, v13, v12
	v_fma_f32 v17, -v9, v16, v13
	v_fmac_f32_e32 v16, v17, v12
	v_fma_f32 v9, -v9, v16, v13
	v_div_fmas_f32 v9, v9, v12, v16
	v_div_fixup_f32 v30, v9, v8, 1.0
	v_mul_f32_e32 v20, v30, v15
	v_mul_f32_e32 v28, v30, v28
	s_waitcnt vmcnt(9)
	v_pk_fma_f32 v[22:23], v[20:21], v[38:39], 0 op_sel_hi:[0,1,0]
	v_pk_fma_f32 v[24:25], v[20:21], v[36:37], 0 op_sel_hi:[0,1,0]
	s_waitcnt vmcnt(8)
	v_pk_fma_f32 v[12:13], v[20:21], v[42:43], 0 op_sel_hi:[0,1,0]
	v_pk_fma_f32 v[20:21], v[20:21], v[40:41], 0 op_sel_hi:[0,1,0]
	s_waitcnt vmcnt(7)
	v_pk_fma_f32 v[24:25], v[28:29], v[44:45], v[24:25] op_sel_hi:[0,1,1]
	v_pk_fma_f32 v[22:23], v[28:29], v[46:47], v[22:23] op_sel_hi:[0,1,1]
	s_waitcnt vmcnt(6)
	v_pk_fma_f32 v[20:21], v[28:29], v[48:49], v[20:21] op_sel_hi:[0,1,1]
	v_pk_fma_f32 v[12:13], v[28:29], v[50:51], v[12:13] op_sel_hi:[0,1,1]
	v_mul_f32_e32 v28, v30, v29
	s_waitcnt vmcnt(5)
	v_pk_fma_f32 v[22:23], v[28:29], v[54:55], v[22:23] op_sel_hi:[0,1,1]
	v_pk_fma_f32 v[24:25], v[28:29], v[52:53], v[24:25] op_sel_hi:[0,1,1]
	v_bfe_u32 v15, v24, 16, 1
	v_add3_u32 v15, v24, v15, s39
	v_lshrrev_b32_e32 v15, 16, v15
	s_waitcnt vmcnt(4)
	v_pk_fma_f32 v[12:13], v[28:29], v[58:59], v[12:13] op_sel_hi:[0,1,1]
	v_pk_fma_f32 v[18:19], v[28:29], v[56:57], v[20:21] op_sel_hi:[0,1,1]
	v_bfe_u32 v16, v25, 16, 1
	v_add3_u32 v16, v25, v16, s39
	v_and_or_b32 v16, v16, s63, v15
	v_bfe_u32 v15, v22, 16, 1
	v_add3_u32 v15, v22, v15, s39
	v_bfe_u32 v17, v23, 16, 1
	v_lshrrev_b32_e32 v15, 16, v15
	v_add3_u32 v17, v23, v17, s39
	v_and_or_b32 v17, v17, s63, v15
	v_bfe_u32 v15, v18, 16, 1
	v_add3_u32 v15, v18, v15, s39
	v_bfe_u32 v18, v19, 16, 1
	v_lshrrev_b32_e32 v15, 16, v15
	v_add3_u32 v18, v19, v18, s39
	v_and_or_b32 v18, v18, s63, v15
	v_bfe_u32 v15, v12, 16, 1
	v_add3_u32 v12, v12, v15, s39
	v_bfe_u32 v15, v13, 16, 1
	v_lshrrev_b32_e32 v12, 16, v12
	v_add3_u32 v13, v13, v15, s39
	v_and_or_b32 v19, v13, s63, v12
	v_lshl_add_u64 v[12:13], s[14:15], 0, v[6:7]
	v_add_co_u32_e32 v12, vcc, 0x31843000, v12
	s_nop 1
	v_addc_co_u32_e32 v13, vcc, 0, v13, vcc
	global_store_dwordx4 v[12:13], v[16:19], off offset:3072
	s_nop 1
	v_max_f32_e32 v16, v60, v60
	v_max_f32_e32 v11, v61, v61
	v_max_f32_e32 v11, v16, v11
	v_sub_f32_e32 v15, v60, v11
	v_sub_f32_e32 v10, v61, v11
	v_mul_f32_e32 v15, 0x3fb8aa3b, v15
	v_mul_f32_e32 v10, 0x3fb8aa3b, v10
	v_exp_f32_e32 v15, v15
	v_exp_f32_e32 v23, v10
	s_nop 0
	v_add_f32_e32 v10, v15, v23
	v_div_scale_f32 v11, s[18:19], v10, v10, 1.0
	v_rcp_f32_e32 v16, v11
	v_readlane_b32 s18, v255, 30
	v_readlane_b32 s19, v255, 31
	s_add_u32 s24, s24, s18
	v_fma_f32 v17, -v11, v16, 1.0
	v_fmac_f32_e32 v16, v17, v16
	v_div_scale_f32 v17, vcc, 1.0, v10, 1.0
	v_mul_f32_e32 v18, v17, v16
	v_fma_f32 v19, -v11, v18, v17
	v_fmac_f32_e32 v18, v19, v16
	v_fma_f32 v11, -v11, v18, v17
	v_div_fmas_f32 v11, v11, v16, v18
	v_div_fixup_f32 v26, v11, v10, 1.0
	v_mul_f32_e32 v22, v15, v26
	v_mul_f32_e32 v26, v23, v26
	s_addc_u32 s25, s25, s19
	v_readlane_b32 s18, v255, 32
	v_readlane_b32 s19, v255, 33
	v_readlane_b32 s13, v255, 23
	s_add_i32 s34, s34, s13
	v_lshl_add_u64 v[2:3], v[2:3], 0, s[18:19]
	v_readlane_b32 s18, v255, 34
	v_readlane_b32 s19, v255, 35
	v_readlane_b32 s13, v255, 25
	s_add_i32 s36, s36, s13
	v_lshl_add_u64 v[4:5], v[4:5], 0, s[18:19]
	v_readlane_b32 s18, v255, 13
	v_readlane_b32 s19, v255, 14
	s_cmpk_gt_i32 s12, 0x1fff
	s_waitcnt vmcnt(2)
	v_pk_mul_f32 v[8:9], v[68:69], v[26:27] op_sel_hi:[1,0]
	v_pk_mul_f32 v[10:11], v[70:71], v[26:27] op_sel_hi:[1,0]
	v_pk_fma_f32 v[30:31], v[64:65], v[22:23], v[8:9] op_sel_hi:[1,0,1]
	v_pk_fma_f32 v[28:29], v[66:67], v[22:23], v[10:11] op_sel_hi:[1,0,1]
	v_bfe_u32 v15, v29, 16, 1
	v_add3_u32 v15, v29, v15, s39
	v_lshl_add_u64 v[6:7], v[6:7], 0, s[18:19]
	s_waitcnt vmcnt(1)
	v_pk_mul_f32 v[16:17], v[76:77], v[26:27] op_sel_hi:[1,0]
	v_pk_mul_f32 v[18:19], v[78:79], v[26:27] op_sel_hi:[1,0]
	s_nop 0
	v_pk_fma_f32 v[18:19], v[74:75], v[22:23], v[18:19] op_sel_hi:[1,0,1]
	v_pk_fma_f32 v[10:11], v[72:73], v[22:23], v[16:17] op_sel_hi:[1,0,1]
	v_bfe_u32 v8, v30, 16, 1
	v_add3_u32 v8, v30, v8, s39
	v_bfe_u32 v9, v31, 16, 1
	v_lshrrev_b32_e32 v8, 16, v8
	v_add3_u32 v9, v31, v9, s39
	v_and_or_b32 v8, v9, s63, v8
	v_bfe_u32 v9, v28, 16, 1
	v_add3_u32 v9, v28, v9, s39
	v_lshrrev_b32_e32 v9, 16, v9
	v_and_or_b32 v9, v15, s63, v9
	v_bfe_u32 v15, v10, 16, 1
	v_add3_u32 v10, v10, v15, s39
	v_bfe_u32 v15, v11, 16, 1
	v_lshrrev_b32_e32 v10, 16, v10
	v_add3_u32 v11, v11, v15, s39
	v_and_or_b32 v10, v11, s63, v10
	v_bfe_u32 v11, v18, 16, 1
	v_add3_u32 v11, v18, v11, s39
	v_bfe_u32 v15, v19, 16, 1
	v_lshrrev_b32_e32 v11, 16, v11
	v_add3_u32 v15, v19, v15, s39
	v_and_or_b32 v11, v15, s63, v11
	global_store_dwordx4 v[12:13], v[8:11], off offset:2048
	s_cbranch_scc1 .LBB0_890
